# plus: stage-3 idle-wave L2 prefetch loads target unused registers and are not waited for before the barrier
# speedup vs baseline: 1.0183x; 1.0012x over previous
; #define LAS __attribute__((address_space(3)))
; __device__ __forceinline__ float bf2f(unsigned short v) { return __uint_as_float(((unsigned)v) << 16); }
; __device__ __forceinline__ unsigned pk2(float lo, float hi) { const f32x2_t v = {lo, hi}; const bf16x2_t b = __builtin_convertvector(v, bf16x2_t); return __builtin_bit_cast(unsigned, b); }
; __device__ __forceinline__ void dn_prep_item(const Args& a, LAS unsigned char* lds, int item, int tid, int wave, int lane, int& cwh, int next_item) {
;     ...
;         const int t2 = tid - 256; const float gl = gcs[63];
; #pragma unroll 4
;         for (int r = 0; r < 32; ++r) { const int idx = t2 + 256 * r, i = idx & 63, d = idx >> 6;
;             const float v = bf2f(*(const LAS unsigned short*)(lds + L_KH + i * KS_ + 2 * d)) * __expf(gl - gcs[i]);
;             *(LAS unsigned short*)(lds + L_KDT + d * AS_ + 2 * i) = (unsigned short)(pk2(v, 0.f) & 0xffffu); }
;         if (next_item >= 0) { const int h2 = next_item & 3, n2 = (next_item >> 2) & (NCH - 1), b2 = next_item >> 9; unsigned d0 = 0u, d1 = 0u;
;             const unsigned char* pb = (const unsigned char*)(P + (size_t)(b2 * T + n2 * 64) * NIN + 1024 + h2 * 128);
;             { const int idx = t2, row = idx / 6, seg = idx % 6; if (n2 > 0 || row >= 3) asm volatile("global_load_dword %0, %1, off" : "+v"(d0) : "v"(pb + (ptrdiff_t)(row - 3) * (NIN * 2) + (seg >> 1) * 1024 + (seg & 1) * 128) : "memory"); }
;             { const int idx = t2 + 256, row = idx / 6, seg = idx % 6; if (idx < 402) asm volatile("global_load_dword %0, %1, off" : "+v"(d1) : "v"(pb + (ptrdiff_t)(row - 3) * (NIN * 2) + (seg >> 1) * 1024 + (seg & 1) * 128) : "memory"); }
.LBB0_870:
	v_add_u32_e32 v122, 0xffffff00, v206
	v_ashrrev_i32_e32 v122, 6, v122
	v_lshl_add_u32 v120, v122, 1, v187
	v_mad_u32_u24 v121, v122, s24, v48
	ds_read_u16 v88, v120
	ds_read_u16 v89, v120 offset:8
	ds_read_u16 v90, v120 offset:16
	ds_read_u16 v91, v120 offset:24
	ds_read_u16 v92, v120 offset:32
	ds_read_u16 v93, v120 offset:40
	ds_read_u16 v94, v120 offset:48
	ds_read_u16 v95, v120 offset:56
	ds_read_u16 v96, v120 offset:64
	ds_read_u16 v97, v120 offset:72
	ds_read_u16 v98, v120 offset:80
	ds_read_u16 v99, v120 offset:88
	ds_read_u16 v100, v120 offset:96
	ds_read_u16 v101, v120 offset:104
	ds_read_u16 v102, v120 offset:112
	ds_read_u16 v103, v120 offset:120
	ds_read_u16 v104, v120 offset:128
	ds_read_u16 v105, v120 offset:136
	ds_read_u16 v106, v120 offset:144
	ds_read_u16 v107, v120 offset:152
	ds_read_u16 v108, v120 offset:160
	ds_read_u16 v109, v120 offset:168
	ds_read_u16 v110, v120 offset:176
	ds_read_u16 v111, v120 offset:184
	ds_read_u16 v112, v120 offset:192
	ds_read_u16 v113, v120 offset:200
	ds_read_u16 v114, v120 offset:208
	ds_read_u16 v115, v120 offset:216
	ds_read_u16 v116, v120 offset:224
	ds_read_u16 v117, v120 offset:232
	ds_read_u16 v118, v120 offset:240
	ds_read_u16 v119, v120 offset:248
	s_waitcnt lgkmcnt(0)
	v_lshlrev_b32_e32 v88, 16, v88
	v_mul_f32_e32 v88, v0, v88
	v_cvt_pk_bf16_f32 v88, v88, s0
	v_lshlrev_b32_e32 v89, 16, v89
	v_mul_f32_e32 v89, v0, v89
	v_cvt_pk_bf16_f32 v89, v89, s0
	v_lshlrev_b32_e32 v90, 16, v90
	v_mul_f32_e32 v90, v0, v90
	v_cvt_pk_bf16_f32 v90, v90, s0
	v_lshlrev_b32_e32 v91, 16, v91
	v_mul_f32_e32 v91, v0, v91
	v_cvt_pk_bf16_f32 v91, v91, s0
	v_lshlrev_b32_e32 v92, 16, v92
	v_mul_f32_e32 v92, v0, v92
	v_cvt_pk_bf16_f32 v92, v92, s0
	v_lshlrev_b32_e32 v93, 16, v93
	v_mul_f32_e32 v93, v0, v93
	v_cvt_pk_bf16_f32 v93, v93, s0
	v_lshlrev_b32_e32 v94, 16, v94
	v_mul_f32_e32 v94, v0, v94
	v_cvt_pk_bf16_f32 v94, v94, s0
	v_lshlrev_b32_e32 v95, 16, v95
	v_mul_f32_e32 v95, v0, v95
	v_cvt_pk_bf16_f32 v95, v95, s0
	v_lshlrev_b32_e32 v96, 16, v96
	v_mul_f32_e32 v96, v0, v96
	v_cvt_pk_bf16_f32 v96, v96, s0
	v_lshlrev_b32_e32 v97, 16, v97
	v_mul_f32_e32 v97, v0, v97
	v_cvt_pk_bf16_f32 v97, v97, s0
	v_lshlrev_b32_e32 v98, 16, v98
	v_mul_f32_e32 v98, v0, v98
	v_cvt_pk_bf16_f32 v98, v98, s0
	v_lshlrev_b32_e32 v99, 16, v99
	v_mul_f32_e32 v99, v0, v99
	v_cvt_pk_bf16_f32 v99, v99, s0
	v_lshlrev_b32_e32 v100, 16, v100
	v_mul_f32_e32 v100, v0, v100
	v_cvt_pk_bf16_f32 v100, v100, s0
	v_lshlrev_b32_e32 v101, 16, v101
	v_mul_f32_e32 v101, v0, v101
	v_cvt_pk_bf16_f32 v101, v101, s0
	v_lshlrev_b32_e32 v102, 16, v102
	v_mul_f32_e32 v102, v0, v102
	v_cvt_pk_bf16_f32 v102, v102, s0
	v_lshlrev_b32_e32 v103, 16, v103
	v_mul_f32_e32 v103, v0, v103
	v_cvt_pk_bf16_f32 v103, v103, s0
	v_lshlrev_b32_e32 v104, 16, v104
	v_mul_f32_e32 v104, v0, v104
	v_cvt_pk_bf16_f32 v104, v104, s0
	v_lshlrev_b32_e32 v105, 16, v105
	v_mul_f32_e32 v105, v0, v105
	v_cvt_pk_bf16_f32 v105, v105, s0
	v_lshlrev_b32_e32 v106, 16, v106
	v_mul_f32_e32 v106, v0, v106
	v_cvt_pk_bf16_f32 v106, v106, s0
	v_lshlrev_b32_e32 v107, 16, v107
	v_mul_f32_e32 v107, v0, v107
	v_cvt_pk_bf16_f32 v107, v107, s0
	v_lshlrev_b32_e32 v108, 16, v108
	v_mul_f32_e32 v108, v0, v108
	v_cvt_pk_bf16_f32 v108, v108, s0
	v_lshlrev_b32_e32 v109, 16, v109
	v_mul_f32_e32 v109, v0, v109
	v_cvt_pk_bf16_f32 v109, v109, s0
	v_lshlrev_b32_e32 v110, 16, v110
	v_mul_f32_e32 v110, v0, v110
	v_cvt_pk_bf16_f32 v110, v110, s0
	v_lshlrev_b32_e32 v111, 16, v111
	v_mul_f32_e32 v111, v0, v111
	v_cvt_pk_bf16_f32 v111, v111, s0
	v_lshlrev_b32_e32 v112, 16, v112
	v_mul_f32_e32 v112, v0, v112
	v_cvt_pk_bf16_f32 v112, v112, s0
	v_lshlrev_b32_e32 v113, 16, v113
	v_mul_f32_e32 v113, v0, v113
	v_cvt_pk_bf16_f32 v113, v113, s0
	v_lshlrev_b32_e32 v114, 16, v114
	v_mul_f32_e32 v114, v0, v114
	v_cvt_pk_bf16_f32 v114, v114, s0
	v_lshlrev_b32_e32 v115, 16, v115
	v_mul_f32_e32 v115, v0, v115
	v_cvt_pk_bf16_f32 v115, v115, s0
	v_lshlrev_b32_e32 v116, 16, v116
	v_mul_f32_e32 v116, v0, v116
	v_cvt_pk_bf16_f32 v116, v116, s0
	v_lshlrev_b32_e32 v117, 16, v117
	v_mul_f32_e32 v117, v0, v117
	v_cvt_pk_bf16_f32 v117, v117, s0
	v_lshlrev_b32_e32 v118, 16, v118
	v_mul_f32_e32 v118, v0, v118
	v_cvt_pk_bf16_f32 v118, v118, s0
	v_lshlrev_b32_e32 v119, 16, v119
	v_mul_f32_e32 v119, v0, v119
	v_cvt_pk_bf16_f32 v119, v119, s0
	ds_write_b16 v121, v88
	ds_write_b16 v121, v89 offset:576
	ds_write_b16 v121, v90 offset:1152
	ds_write_b16 v121, v91 offset:1728
	ds_write_b16 v121, v92 offset:2304
	ds_write_b16 v121, v93 offset:2880
	ds_write_b16 v121, v94 offset:3456
	ds_write_b16 v121, v95 offset:4032
	ds_write_b16 v121, v96 offset:4608
	ds_write_b16 v121, v97 offset:5184
	ds_write_b16 v121, v98 offset:5760
	ds_write_b16 v121, v99 offset:6336
	ds_write_b16 v121, v100 offset:6912
	ds_write_b16 v121, v101 offset:7488
	ds_write_b16 v121, v102 offset:8064
	ds_write_b16 v121, v103 offset:8640
	ds_write_b16 v121, v104 offset:9216
	ds_write_b16 v121, v105 offset:9792
	ds_write_b16 v121, v106 offset:10368
	ds_write_b16 v121, v107 offset:10944
	ds_write_b16 v121, v108 offset:11520
	ds_write_b16 v121, v109 offset:12096
	ds_write_b16 v121, v110 offset:12672
	ds_write_b16 v121, v111 offset:13248
	ds_write_b16 v121, v112 offset:13824
	ds_write_b16 v121, v113 offset:14400
	ds_write_b16 v121, v114 offset:14976
	ds_write_b16 v121, v115 offset:15552
	ds_write_b16 v121, v116 offset:16128
	ds_write_b16 v121, v117 offset:16704
	ds_write_b16 v121, v118 offset:17280
	ds_write_b16 v121, v119 offset:17856
	s_cmp_gt_i32 s38, -1
	s_cbranch_scc0 .LBB0_877
	s_bfe_u32 s41, s38, 0x70002
	s_lshl_b32 s22, s38, 4
	s_and_b32 s22, s22, 0x7fffe000
	s_lshl_b32 s23, s41, 6
	s_or_b32 s22, s23, s22
	s_mul_hi_u32 s23, s22, 0x1800
	s_mulk_i32 s22, 0x1800
	s_add_u32 s22, s10, s22
	s_addc_u32 s23, s11, s23
	s_lshl_b32 s42, s38, 8
	s_and_b32 s42, s42, 0x300
	s_add_u32 s22, s22, s42
	s_addc_u32 s23, s23, 0
	s_cmp_lg_u32 s41, 0
	v_readlane_b32 s86, v244, 49
	s_cselect_b64 s[42:43], -1, 0
	v_readlane_b32 s87, v244, 50
	s_or_b64 s[42:43], s[42:43], s[86:87]
	v_mov_b32_e32 v0, 0
	v_mov_b32_e32 v1, 0
	s_and_saveexec_b64 s[86:87], s[42:43]
	s_cbranch_execz .LBB0_874
	v_lshl_add_u64 v[2:3], s[22:23], 0, v[50:51]
	v_lshl_add_u64 v[2:3], v[2:3], 0, v[52:53]
	s_movk_i32 s42, 0xc000
	v_lshl_add_u64 v[2:3], v[2:3], 0, v[54:55]
	s_mov_b32 s43, -1
	v_lshl_add_u64 v[2:3], v[2:3], 0, s[42:43]
	global_load_dword v245, v[2:3], off
